# DF loops stage the next tile after the stop-flag test (a stopping unit issues no LDS-DMA); landed-before-exchange waits kept
# baseline (speedup 1.0000x reference)
.LBB0_404:
	s_mov_b32 s97, s96
	s_waitcnt lgkmcnt(0)
	v_cmp_eq_u64_e64 s[8:9], s[96:97], v[14:15]
	s_and_b64 vcc, exec, s[8:9]
	s_cbranch_vccnz .LBB0_420
	s_cmp_lt_i32 s80, 0
	s_cbranch_scc1 .Ldfst_l1
	s_and_b32 s92, s27, 0xc000
	s_cmp_gt_i32 s24, 1
	s_cselect_b32 s93, -2, 3
	s_add_i32 s93, s93, s24
	s_lshl_b32 s93, s93, 14
	s_lshl_b64 s[90:91], s[80:81], 14
	v_lshl_add_u64 v[80:81], v[180:181], 0, s[90:91]
	s_add_i32 s92, s76, s92
	s_mov_b32 m0, s92
	s_nop 0
	global_load_lds_dwordx4 v[80:81], off
	v_lshl_add_u64 v[80:81], v[80:81], 0, s[88:89]
	s_addk_i32 s92, 0x2000
	s_mov_b32 m0, s92
	s_nop 0
	global_load_lds_dwordx4 v[80:81], off
	v_lshl_add_u64 v[80:81], v[182:183], 0, s[90:91]
	s_add_i32 s92, s31, s93
	s_mov_b32 m0, s92
	s_nop 0
	global_load_lds_dwordx4 v[80:81], off
	v_lshl_add_u64 v[80:81], v[80:81], 0, s[88:89]
	s_addk_i32 s92, 0x2000
	s_mov_b32 m0, s92
	s_nop 0
	global_load_lds_dwordx4 v[80:81], off
.Ldfst_l1:
	s_cmp_gt_i32 s12, s21
	s_cbranch_scc1 .LBB0_417
	s_xor_b64 s[12:13], s[10:11], -1
	s_add_i32 s10, s27, 0xffff4000
	s_and_b32 s10, s10, 0xc000
	s_add_i32 s14, s34, s10
	v_add_u32_e32 v0, s14, v222
	s_mov_b64 s[10:11], -1
	s_and_b64 vcc, exec, s[12:13]
	v_add_u32_e32 v202, v0, v223
	v_add_u32_e32 v15, v0, v224
	v_add_u32_e32 v14, v0, v225
	v_add_u32_e32 v0, v0, v233
	s_cbranch_vccz .LBB0_408
	ds_read_b128 v[80:83], v202
	ds_read_b128 v[84:87], v202 offset:4096
	ds_read_b128 v[148:151], v15
	ds_read_b128 v[204:207], v15 offset:4096
	ds_read_b128 v[208:211], v14
	ds_read_b128 v[212:215], v14 offset:4096
	ds_read_b128 v[238:241], v0
	ds_read_b128 v[242:245], v0 offset:4096
	s_waitcnt lgkmcnt(7)
	v_mfma_f32_32x32x16_bf16 v[96:111], v[80:83], v[136:139], 0
	s_mov_b64 s[10:11], 0
	s_waitcnt lgkmcnt(6)
	v_mfma_f32_32x32x16_bf16 v[80:95], v[84:87], v[136:139], 0
	s_waitcnt lgkmcnt(5)
	v_mfma_f32_32x32x16_bf16 v[96:111], v[148:151], v[128:131], v[96:111]
	s_waitcnt lgkmcnt(4)
	v_mfma_f32_32x32x16_bf16 v[80:95], v[204:207], v[128:131], v[80:95]
	s_waitcnt lgkmcnt(3)
	v_mfma_f32_32x32x16_bf16 v[96:111], v[208:211], v[140:143], v[96:111]
	s_waitcnt lgkmcnt(2)
	v_mfma_f32_32x32x16_bf16 v[80:95], v[212:215], v[140:143], v[80:95]
	s_waitcnt lgkmcnt(1)
	v_mfma_f32_32x32x16_bf16 v[96:111], v[238:241], v[132:135], v[96:111]
	s_waitcnt lgkmcnt(0)
	v_mfma_f32_32x32x16_bf16 v[80:95], v[242:245], v[132:135], v[80:95]

.LBB0_437:
	s_mov_b32 s97, s96
	s_waitcnt lgkmcnt(0)
	v_cmp_eq_u64_e64 s[8:9], s[96:97], v[2:3]
	s_and_b64 vcc, exec, s[8:9]
	s_cbranch_vccnz .LBB0_449
	s_cmp_lt_i32 s15, 3
	s_cbranch_scc1 .Ldfst_e1
	s_and_b32 s28, s13, 0xc000
	s_cmp_gt_i32 s14, 1
	s_cselect_b32 s29, -2, 3
	s_add_i32 s29, s29, s14
	s_add_i32 s80, s10, -4
	s_lshl_b32 s29, s29, 14
	s_lshl_b64 s[26:27], s[80:81], 14
	v_lshl_add_u64 v[4:5], v[180:181], 0, s[26:27]
	s_add_i32 s28, s76, s28
	s_mov_b32 m0, s28
	s_nop 0
	global_load_lds_dwordx4 v[4:5], off
	v_lshl_add_u64 v[4:5], v[4:5], 0, s[88:89]
	s_addk_i32 s28, 0x2000
	s_mov_b32 m0, s28
	s_nop 0
	global_load_lds_dwordx4 v[4:5], off
	v_lshl_add_u64 v[4:5], v[182:183], 0, s[26:27]
	s_add_i32 s28, s31, s29
	s_mov_b32 m0, s28
	s_nop 0
	global_load_lds_dwordx4 v[4:5], off
	v_lshl_add_u64 v[4:5], v[4:5], 0, s[88:89]
	s_addk_i32 s28, 0x2000
	s_mov_b32 m0, s28
	s_nop 0
	global_load_lds_dwordx4 v[4:5], off
.Ldfst_e1:
	s_cmp_gt_i32 s15, s21
	s_cbranch_scc1 .LBB0_446
	s_add_i32 s8, s13, 0xffff4000
	s_and_b32 s8, s8, 0xc000
	v_add_u32_e32 v0, s8, v221
	v_add_u32_e32 v6, v0, v222
	v_add_u32_e32 v14, v0, v223
	ds_read_b128 v[2:5], v6
	ds_read_b128 v[6:9], v6 offset:4096
	ds_read_b128 v[10:13], v14
	ds_read_b128 v[128:131], v14 offset:4096
	v_add_u32_e32 v14, v0, v224
	v_add_u32_e32 v0, v0, v219
	ds_read_b128 v[132:135], v14
	ds_read_b128 v[136:139], v14 offset:4096
	ds_read_b128 v[144:147], v0
	ds_read_b128 v[148:151], v0 offset:4096
	s_add_i32 s8, s12, s10
	s_lshl_b32 s9, s14, 14
	s_waitcnt lgkmcnt(7)
	v_mfma_f32_32x32x16_bf16 v[96:111], v[2:5], v[112:115], 0
	v_add_u32_e32 v235, s9, v220
	s_waitcnt lgkmcnt(6)
	v_mfma_f32_32x32x16_bf16 v[80:95], v[6:9], v[112:115], 0
	s_waitcnt lgkmcnt(5)
	v_mfma_f32_32x32x16_bf16 v[96:111], v[10:13], v[116:119], v[96:111]
	s_waitcnt lgkmcnt(4)
	v_mfma_f32_32x32x16_bf16 v[80:95], v[128:131], v[116:119], v[80:95]
	ds_read_b64_tr_b16 v[6:7], v235
	ds_read_b64_tr_b16 v[8:9], v235 offset:512
	ds_read_b64_tr_b16 v[2:3], v235 offset:1024
	ds_read_b64_tr_b16 v[4:5], v235 offset:1536
	ds_read_b64_tr_b16 v[140:141], v235 offset:4096
	ds_read_b64_tr_b16 v[142:143], v235 offset:4608
	ds_read_b64_tr_b16 v[128:129], v235 offset:5120
	ds_read_b64_tr_b16 v[130:131], v235 offset:5632
	s_waitcnt lgkmcnt(11)
	v_mfma_f32_32x32x16_bf16 v[96:111], v[132:135], v[120:123], v[96:111]
	s_waitcnt lgkmcnt(10)
	v_mfma_f32_32x32x16_bf16 v[80:95], v[136:139], v[120:123], v[80:95]
	s_waitcnt lgkmcnt(9)
	v_mfma_f32_32x32x16_bf16 v[96:111], v[144:147], v[124:127], v[96:111]
	ds_read_b64_tr_b16 v[136:137], v235 offset:2048
	ds_read_b64_tr_b16 v[138:139], v235 offset:2560
	ds_read_b64_tr_b16 v[10:11], v235 offset:3072
	ds_read_b64_tr_b16 v[12:13], v235 offset:3584
	ds_read_b64_tr_b16 v[144:145], v235 offset:6144
	ds_read_b64_tr_b16 v[146:147], v235 offset:6656
	ds_read_b64_tr_b16 v[132:133], v235 offset:7168
	ds_read_b64_tr_b16 v[134:135], v235 offset:7680
	s_waitcnt lgkmcnt(14)
	v_mfma_f32_32x32x16_bf16 v[80:95], v[148:151], v[124:127], v[80:95]
	v_add_u32_e32 v0, v233, v218
	v_cvt_f32_i32_e32 v0, v0
	s_cmp_lg_u32 s8, 1
	s_mov_b64 s[8:9], -1
	s_cbranch_scc0 .LBB0_441
	v_add_f32_e32 v14, 0, v96
	v_subrev_f32_e32 v15, s4, v97
	s_nop 4
	v_fma_f32 v186, s2, v196, v80
	v_fma_f32 v187, s3, v197, v81
	v_fma_f32 v184, s2, v226, v98
	v_fma_f32 v185, s3, v227, v99
	v_max_f32_e32 v148, v14, v186
	v_max_f32_e32 v149, v15, v187
	v_fma_f32 v188, s2, v152, v82
	v_fma_f32 v189, s3, v153, v83
	v_max3_f32 v148, v148, s82, v149
	v_max_f32_e32 v149, v184, v188
	v_max_f32_e32 v150, v185, v189
	v_fma_f32 v190, s2, v154, v100
	v_fma_f32 v191, s3, v155, v101
	v_fma_f32 v192, s2, v156, v84
	v_fma_f32 v193, s3, v157, v85
	v_max3_f32 v148, v148, v149, v150
	v_max_f32_e32 v149, v190, v192
	v_max_f32_e32 v150, v191, v193
	v_fma_f32 v194, s2, v158, v102
	v_fma_f32 v195, s3, v159, v103
	v_fma_f32 v198, s2, v160, v86
	v_fma_f32 v199, s3, v161, v87
	v_max3_f32 v148, v148, v149, v150
	v_max_f32_e32 v149, v194, v198
	v_max_f32_e32 v150, v195, v199
	v_fma_f32 v200, s2, v162, v104
	v_fma_f32 v201, s3, v163, v105
	v_fma_f32 v202, s2, v164, v88
	v_fma_f32 v203, s3, v165, v89
	v_max3_f32 v148, v148, v149, v150
	v_max_f32_e32 v149, v200, v202
	v_max_f32_e32 v150, v201, v203
	v_fma_f32 v204, s2, v166, v106
	v_fma_f32 v205, s3, v167, v107
	v_fma_f32 v206, s2, v168, v90
	v_fma_f32 v207, s3, v169, v91
	v_max3_f32 v148, v148, v149, v150
	v_max_f32_e32 v149, v204, v206
	v_max_f32_e32 v150, v205, v207
	v_fma_f32 v208, s2, v170, v108
	v_fma_f32 v209, s3, v171, v109
	v_fma_f32 v210, s2, v172, v92
	v_fma_f32 v211, s3, v173, v93
	v_max3_f32 v148, v148, v149, v150
	v_max_f32_e32 v149, v208, v210
	v_max_f32_e32 v150, v209, v211
	v_fma_f32 v212, s2, v174, v110
	v_fma_f32 v213, s3, v175, v111
	v_fma_f32 v214, s2, v176, v94
	v_fma_f32 v215, s3, v177, v95
	v_max3_f32 v148, v148, v149, v150
	v_max_f32_e32 v149, v212, v214
	v_max_f32_e32 v150, v213, v215
	v_max3_f32 v237, v148, v149, v150
	v_mul_f32_e32 v236, s4, v0
	s_mov_b64 s[8:9], 0
